# P4 epilogue: rows 0-3 row-stat loads issued in the last K-iteration ahead of the next tile's prefetch DMA; rows 4-7 reduced after round 3
# speedup vs baseline: 1.0194x; 1.0035x over previous
; #define PG8_STAGE(bufoff, gbase, voff) do { _Pragma("unroll") for (int _i = 0; _i < 2; ++_i) \
;         __builtin_amdgcn_global_load_lds((const unsigned*)((const char*)(gbase) + (voff)[_i]), (PG8_LAS unsigned*)(lds + (bufoff) + ldsw + _i * 8192), 16, 0, 0); } while (0)
; #define PG8_LDA(dst, b, h) do { _Pragma("unroll") for (int m = 0; m < 4; ++m) _Pragma("unroll") for (int k = 0; k < 2; ++k) dst[m][k] = *(const PG8_LAS bf16x8*)(lds + PG8_SA(b, h) + aoff + m * 2048 + k * 1024); } while (0)
; #define PG8_LDB(dst, b, h) do { _Pragma("unroll") for (int n = 0; n < 2; ++n) _Pragma("unroll") for (int k = 0; k < 2; ++k) dst[n][k] = *(const PG8_LAS bf16x8*)(lds + PG8_SB(b, h) + boff + n * 2048 + k * 1024); } while (0)
; #define PG8_MMA(ai, bj, At, Bt) do { __builtin_amdgcn_s_setprio(1); _Pragma("unroll") for (int m = 0; m < 4; ++m) _Pragma("unroll") for (int n = 0; n < 2; ++n) _Pragma("unroll") for (int k = 0; k < 2; ++k) \
;         acc[ai][bj][m][n] = __builtin_amdgcn_mfma_f32_16x16x32_bf16(Bt[n][k], At[m][k], acc[ai][bj][m][n], 0, 0, 0); __builtin_amdgcn_s_setprio(0); } while (0)
; #define PG8_WAIT_V(n) asm volatile("s_waitcnt vmcnt(" #n ")" ::: "memory")
; #define PG8_BAR __builtin_amdgcn_s_barrier()
; template <class Epi, class Sched, bool ALIGN_EPI = false, bool SP2 = false>
; __device__ __forceinline__ void gemm_phase(PG8_LAS unsigned char* lds, const Gemm g, const Sched& S, const Epi& E) {
;     ...
;         for (int t = 0; t < nt; t += 2) {
;             const bool last = (t == nt - 2);
;             const char* a1 = cA + (size_t)(t + 1) * kstep;
;             const char* a2 = last ? nA : cA + (size_t)(t + 2) * kstep; const char* b2 = last ? nB : cB + (size_t)(t + 2) * kstep;
;             const char* a3 = a2 + kstep; const char* b3 = b2 + kstep;
;             if (last && has_next) S.a_ready(nxt);
;             if constexpr (SP2) {
;             PG8_LDB(B0, 0, 0); PG8_LDB(B1, 0, 1); PG8_SCHED; PG8_LDA(At, 0, 0); PG8_STAGE(PG8_SA(1, 1), a1 + hstep, voffA);
;             PG8_WAIT_V(8); PG8_WAIT_L(0); PG8_BAR; PG8_MMA(0, 0, At, B0); PG8_MMA(0, 1, At, B1); PG8_BAR; PG8_SCHED;
;             PG8_LDA(At, 0, 1); PG8_STAGE(PG8_SB(0, 0), b2, voffB); PG8_STAGE(PG8_SB(0, 1), b2 + hstep, voffB); PG8_STAGE(PG8_SA(0, 0), a2, voffA);
;             PG8_WAIT_V(8); PG8_WAIT_L(0); PG8_BAR; PG8_MMA(1, 0, At, B0); PG8_MMA(1, 1, At, B1); PG8_BAR; PG8_SCHED;
.LBB0_1152:
	s_add_u32 s26, s24, 0xfffc0080
	s_addc_u32 s27, s25, -1
	s_add_i32 s76, 0, 0x10000
	s_cmp_eq_u32 s93, 12
	s_cselect_b32 s43, s75, s27
	s_cselect_b32 s42, s89, s26
	s_cselect_b32 s27, s61, s37
	s_cselect_b32 s26, s92, s36
	s_add_i32 s77, 0, 0x14000
	v_add_u32_e32 v166, s76, v155
	v_add_u32_e32 v182, s77, v155
	ds_read_b128 v[150:153], v166
	ds_read_b128 v[158:161], v166 offset:1024
	ds_read_b128 v[162:165], v166 offset:2048
	ds_read_b128 v[166:169], v166 offset:3072
	ds_read_b128 v[170:173], v182
	ds_read_b128 v[174:177], v182 offset:1024
	ds_read_b128 v[178:181], v182 offset:2048
	ds_read_b128 v[182:185], v182 offset:3072
	v_lshl_add_u64 v[202:203], s[24:25], 0, v[134:135]
	s_add_i32 m0, s49, 0xc000
	ds_read_b128 v[186:189], v157
	ds_read_b128 v[190:193], v157 offset:1024
	ds_read_b128 v[194:197], v157 offset:2048
	ds_read_b128 v[198:201], v157 offset:3072
	ds_read_b128 v[208:211], v157 offset:4096
	ds_read_b128 v[212:215], v157 offset:5120
	ds_read_b128 v[216:219], v157 offset:6144
	ds_read_b128 v[220:223], v157 offset:7168
	global_load_lds_dwordx4 v[202:203], off
	v_lshl_add_u64 v[202:203], s[24:25], 0, v[148:149]
	s_add_i32 m0, s49, 0xe000
	s_nop 0
	global_load_lds_dwordx4 v[202:203], off
	s_waitcnt vmcnt(8)
	s_waitcnt lgkmcnt(0)
	s_barrier
	s_setprio 1
	s_waitcnt lgkmcnt(0)
	v_mfma_f32_16x16x32_bf16 v[124:127], v[150:153], v[186:189], v[124:127]
	v_mfma_f32_16x16x32_bf16 v[120:123], v[162:165], v[186:189], v[120:123]
	v_mfma_f32_16x16x32_bf16 v[108:111], v[150:153], v[194:197], v[108:111]
	v_mfma_f32_16x16x32_bf16 v[104:107], v[162:165], v[194:197], v[104:107]
	v_mfma_f32_16x16x32_bf16 v[92:95], v[150:153], v[208:211], v[92:95]
	v_mfma_f32_16x16x32_bf16 v[88:91], v[162:165], v[208:211], v[88:91]
	v_mfma_f32_16x16x32_bf16 v[76:79], v[150:153], v[216:219], v[76:79]
	v_mfma_f32_16x16x32_bf16 v[72:75], v[162:165], v[216:219], v[72:75]
	v_mfma_f32_16x16x32_bf16 v[124:127], v[158:161], v[190:193], v[124:127]
	v_mfma_f32_16x16x32_bf16 v[120:123], v[166:169], v[190:193], v[120:123]
	v_mfma_f32_16x16x32_bf16 v[108:111], v[158:161], v[198:201], v[108:111]
	v_mfma_f32_16x16x32_bf16 v[104:107], v[166:169], v[198:201], v[104:107]
	v_mfma_f32_16x16x32_bf16 v[92:95], v[158:161], v[212:215], v[92:95]
	v_mfma_f32_16x16x32_bf16 v[88:91], v[166:169], v[212:215], v[88:91]
	v_mfma_f32_16x16x32_bf16 v[76:79], v[158:161], v[220:223], v[76:79]
	v_mfma_f32_16x16x32_bf16 v[72:75], v[166:169], v[220:223], v[72:75]
	s_setprio 0
	s_setprio 1
	v_mfma_f32_16x16x32_bf16 v[116:119], v[170:173], v[186:189], v[116:119]
	v_mfma_f32_16x16x32_bf16 v[112:115], v[178:181], v[186:189], v[112:115]
	v_mfma_f32_16x16x32_bf16 v[100:103], v[170:173], v[194:197], v[100:103]
	v_mfma_f32_16x16x32_bf16 v[96:99], v[178:181], v[194:197], v[96:99]
	v_mfma_f32_16x16x32_bf16 v[84:87], v[170:173], v[208:211], v[84:87]
	v_mfma_f32_16x16x32_bf16 v[80:83], v[178:181], v[208:211], v[80:83]
	v_mfma_f32_16x16x32_bf16 v[68:71], v[170:173], v[216:219], v[68:71]
	v_mfma_f32_16x16x32_bf16 v[64:67], v[178:181], v[216:219], v[64:67]
	v_mfma_f32_16x16x32_bf16 v[116:119], v[174:177], v[190:193], v[116:119]
	v_mfma_f32_16x16x32_bf16 v[112:115], v[182:185], v[190:193], v[112:115]
	v_mfma_f32_16x16x32_bf16 v[100:103], v[174:177], v[198:201], v[100:103]
	v_mfma_f32_16x16x32_bf16 v[96:99], v[182:185], v[198:201], v[96:99]
	v_mfma_f32_16x16x32_bf16 v[84:87], v[174:177], v[212:215], v[84:87]
	v_mfma_f32_16x16x32_bf16 v[80:83], v[182:185], v[212:215], v[80:83]
	v_mfma_f32_16x16x32_bf16 v[68:71], v[174:177], v[220:223], v[68:71]
	v_mfma_f32_16x16x32_bf16 v[64:67], v[182:185], v[220:223], v[64:67]
	s_setprio 0
	s_barrier
	s_add_i32 s76, s76, s48
	v_lshl_add_u64 v[202:203], s[26:27], 0, v[138:139]
	s_mov_b32 m0, s76
	ds_read_b128 v[186:189], v157 offset:16384
	ds_read_b128 v[190:193], v157 offset:17408
	ds_read_b128 v[194:197], v157 offset:18432
	ds_read_b128 v[198:201], v157 offset:19456
	ds_read_b128 v[208:211], v157 offset:20480
	ds_read_b128 v[212:215], v157 offset:21504
	ds_read_b128 v[216:219], v157 offset:22528
	ds_read_b128 v[220:223], v157 offset:23552
	global_load_lds_dwordx4 v[202:203], off
	s_add_i32 m0, s76, 0x2000
	s_add_u32 s94, s26, 0x40000
	v_lshl_add_u64 v[224:225], s[26:27], 0, v[128:129]
	s_addc_u32 s95, s27, 0
	s_add_i32 s76, s77, s48
	global_load_lds_dwordx4 v[224:225], off
	v_lshl_add_u64 v[226:227], s[94:95], 0, v[138:139]
	s_mov_b32 m0, s76
	v_lshl_add_u64 v[228:229], s[42:43], 0, v[130:131]
	global_load_lds_dwordx4 v[226:227], off
	v_lshl_add_u64 v[226:227], s[94:95], 0, v[128:129]
	s_add_i32 m0, s76, 0x2000
	s_nop 0
	global_load_lds_dwordx4 v[226:227], off
	v_lshl_add_u64 v[226:227], s[42:43], 0, v[132:133]
	s_mov_b32 m0, s49
	s_nop 0
	global_load_lds_dwordx4 v[226:227], off
	s_mov_b32 m0, s52
	s_nop 0
	global_load_lds_dwordx4 v[228:229], off
	s_waitcnt vmcnt(8)
	s_waitcnt lgkmcnt(0)
	s_barrier
; #define PG8_STAGE(bufoff, gbase, voff) do { _Pragma("unroll") for (int _i = 0; _i < 2; ++_i) \
;         __builtin_amdgcn_global_load_lds((const unsigned*)((const char*)(gbase) + (voff)[_i]), (PG8_LAS unsigned*)(lds + (bufoff) + ldsw + _i * 8192), 16, 0, 0); } while (0)
; #define PG8_LDA(dst, b, h) do { _Pragma("unroll") for (int m = 0; m < 4; ++m) _Pragma("unroll") for (int k = 0; k < 2; ++k) dst[m][k] = *(const PG8_LAS bf16x8*)(lds + PG8_SA(b, h) + aoff + m * 2048 + k * 1024); } while (0)
; #define PG8_LDB(dst, b, h) do { _Pragma("unroll") for (int n = 0; n < 2; ++n) _Pragma("unroll") for (int k = 0; k < 2; ++k) dst[n][k] = *(const PG8_LAS bf16x8*)(lds + PG8_SB(b, h) + boff + n * 2048 + k * 1024); } while (0)
; #define PG8_MMA(ai, bj, At, Bt) do { __builtin_amdgcn_s_setprio(1); _Pragma("unroll") for (int m = 0; m < 4; ++m) _Pragma("unroll") for (int n = 0; n < 2; ++n) _Pragma("unroll") for (int k = 0; k < 2; ++k) \
;         acc[ai][bj][m][n] = __builtin_amdgcn_mfma_f32_16x16x32_bf16(Bt[n][k], At[m][k], acc[ai][bj][m][n], 0, 0, 0); __builtin_amdgcn_s_setprio(0); } while (0)
; #define PG8_WAIT_V(n) asm volatile("s_waitcnt vmcnt(" #n ")" ::: "memory")
; #define PG8_WAIT_L(n) asm volatile("s_waitcnt lgkmcnt(" #n ")" ::: "memory")
;     __device__ __forceinline__ void operator()(const f32x4 (&acc)[2][2][4][2], const Unit& u, int wr, int wc, int fr, int fq) const {
;     ...
;                 const f32x4* sp = (const f32x4*)(ss + (size_t)row * 16);
;                 const f32x4 a0 = sp[0], a1 = sp[1], a2 = sp[2], a3 = sp[3];
; template <class Epi, class Sched, bool ALIGN_EPI = false, bool SP2 = false>
; __device__ __forceinline__ void gemm_phase(PG8_LAS unsigned char* lds, const Gemm g, const Sched& S, const Epi& E) {
;     ...
;             PG8_WAIT_V(8); PG8_WAIT_L(0); PG8_BAR; PG8_MMA(1, 0, At, B0); PG8_MMA(1, 1, At, B1); PG8_BAR; PG8_SCHED;
;             PG8_LDB(B0, 1, 0); PG8_LDB(B1, 1, 1); PG8_SCHED; PG8_LDA(At, 1, 0); PG8_STAGE(PG8_SA(0, 1), a2 + hstep, voffA);
;             PG8_WAIT_V(8); PG8_WAIT_L(0); PG8_BAR; PG8_MMA(0, 0, At, B0); PG8_MMA(0, 1, At, B1); PG8_BAR; PG8_SCHED;
;             PG8_LDA(At, 1, 1); PG8_STAGE(PG8_SB(1, 0), b3, voffB); PG8_STAGE(PG8_SB(1, 1), b3 + hstep, voffB); PG8_STAGE(PG8_SA(1, 0), a3, voffA);
;             PG8_WAIT_V(8); PG8_WAIT_L(0); PG8_BAR; PG8_MMA(1, 0, At, B0); PG8_MMA(1, 1, At, B1); PG8_BAR; PG8_SCHED;
	s_setprio 1
	s_waitcnt lgkmcnt(0)
	v_mfma_f32_16x16x32_bf16 v[60:63], v[150:153], v[186:189], v[60:63]
	v_mfma_f32_16x16x32_bf16 v[56:59], v[162:165], v[186:189], v[56:59]
	v_mfma_f32_16x16x32_bf16 v[44:47], v[150:153], v[194:197], v[44:47]
	v_mfma_f32_16x16x32_bf16 v[40:43], v[162:165], v[194:197], v[40:43]
	v_mfma_f32_16x16x32_bf16 v[28:31], v[150:153], v[208:211], v[28:31]
	v_mfma_f32_16x16x32_bf16 v[24:27], v[162:165], v[208:211], v[24:27]
	v_mfma_f32_16x16x32_bf16 v[12:15], v[150:153], v[216:219], v[12:15]
	v_mfma_f32_16x16x32_bf16 v[8:11], v[162:165], v[216:219], v[8:11]
	v_mfma_f32_16x16x32_bf16 v[60:63], v[158:161], v[190:193], v[60:63]
	v_mfma_f32_16x16x32_bf16 v[56:59], v[166:169], v[190:193], v[56:59]
	v_mfma_f32_16x16x32_bf16 v[44:47], v[158:161], v[198:201], v[44:47]
	v_mfma_f32_16x16x32_bf16 v[40:43], v[166:169], v[198:201], v[40:43]
	v_mfma_f32_16x16x32_bf16 v[28:31], v[158:161], v[212:215], v[28:31]
	v_mfma_f32_16x16x32_bf16 v[24:27], v[166:169], v[212:215], v[24:27]
	v_mfma_f32_16x16x32_bf16 v[12:15], v[158:161], v[220:223], v[12:15]
	v_mfma_f32_16x16x32_bf16 v[8:11], v[166:169], v[220:223], v[8:11]
	s_setprio 0
	s_setprio 1
	v_mfma_f32_16x16x32_bf16 v[52:55], v[170:173], v[186:189], v[52:55]
	v_mfma_f32_16x16x32_bf16 v[48:51], v[178:181], v[186:189], v[48:51]
	v_mfma_f32_16x16x32_bf16 v[36:39], v[170:173], v[194:197], v[36:39]
	v_mfma_f32_16x16x32_bf16 v[32:35], v[178:181], v[194:197], v[32:35]
	v_mfma_f32_16x16x32_bf16 v[20:23], v[170:173], v[208:211], v[20:23]
	v_mfma_f32_16x16x32_bf16 v[16:19], v[178:181], v[208:211], v[16:19]
	v_mfma_f32_16x16x32_bf16 v[4:7], v[170:173], v[216:219], v[4:7]
	v_mfma_f32_16x16x32_bf16 v[0:3], v[178:181], v[216:219], v[0:3]
	v_mfma_f32_16x16x32_bf16 v[52:55], v[174:177], v[190:193], v[52:55]
	v_mfma_f32_16x16x32_bf16 v[48:51], v[182:185], v[190:193], v[48:51]
	v_mfma_f32_16x16x32_bf16 v[36:39], v[174:177], v[198:201], v[36:39]
	v_mfma_f32_16x16x32_bf16 v[32:35], v[182:185], v[198:201], v[32:35]
	v_mfma_f32_16x16x32_bf16 v[20:23], v[174:177], v[212:215], v[20:23]
	v_mfma_f32_16x16x32_bf16 v[16:19], v[182:185], v[212:215], v[16:19]
	v_mfma_f32_16x16x32_bf16 v[4:7], v[174:177], v[220:223], v[4:7]
	v_mfma_f32_16x16x32_bf16 v[0:3], v[182:185], v[220:223], v[0:3]
	s_setprio 0
	s_barrier
	s_add_i32 s76, 0, 0x18000
	s_add_i32 s77, 0, 0x1c000
	v_add_u32_e32 v166, s76, v155
	v_add_u32_e32 v182, s77, v155
	ds_read_b128 v[150:153], v166
	ds_read_b128 v[158:161], v166 offset:1024
	ds_read_b128 v[162:165], v166 offset:2048
	ds_read_b128 v[166:169], v166 offset:3072
	ds_read_b128 v[170:173], v182
	ds_read_b128 v[174:177], v182 offset:1024
	ds_read_b128 v[178:181], v182 offset:2048
	ds_read_b128 v[182:185], v182 offset:3072
	s_add_u32 s42, s42, 0x40000
	s_addc_u32 s43, s43, 0
	s_mov_b32 m0, s53
	v_lshl_add_u64 v[230:231], s[42:43], 0, v[132:133]
	ds_read_b128 v[186:189], v157 offset:32768
	ds_read_b128 v[190:193], v157 offset:33792
	ds_read_b128 v[194:197], v157 offset:34816
	ds_read_b128 v[198:201], v157 offset:35840
	ds_read_b128 v[208:211], v157 offset:36864
	ds_read_b128 v[212:215], v157 offset:37888
	ds_read_b128 v[216:219], v157 offset:38912
	ds_read_b128 v[220:223], v157 offset:39936
	global_load_lds_dwordx4 v[230:231], off
	v_lshl_add_u64 v[230:231], s[42:43], 0, v[130:131]
	s_mov_b32 m0, s54
	s_nop 0
	global_load_lds_dwordx4 v[230:231], off
	s_waitcnt vmcnt(8)
	s_waitcnt lgkmcnt(0)
	s_barrier
	s_setprio 1
	s_waitcnt lgkmcnt(0)
	v_mfma_f32_16x16x32_bf16 v[124:127], v[150:153], v[186:189], v[124:127]
	v_mfma_f32_16x16x32_bf16 v[120:123], v[162:165], v[186:189], v[120:123]
	v_mfma_f32_16x16x32_bf16 v[108:111], v[150:153], v[194:197], v[108:111]
	v_mfma_f32_16x16x32_bf16 v[104:107], v[162:165], v[194:197], v[104:107]
	v_mfma_f32_16x16x32_bf16 v[92:95], v[150:153], v[208:211], v[92:95]
	v_mfma_f32_16x16x32_bf16 v[88:91], v[162:165], v[208:211], v[88:91]
	v_mfma_f32_16x16x32_bf16 v[76:79], v[150:153], v[216:219], v[76:79]
	v_mfma_f32_16x16x32_bf16 v[72:75], v[162:165], v[216:219], v[72:75]
	v_mfma_f32_16x16x32_bf16 v[124:127], v[158:161], v[190:193], v[124:127]
	v_mfma_f32_16x16x32_bf16 v[120:123], v[166:169], v[190:193], v[120:123]
	v_mfma_f32_16x16x32_bf16 v[108:111], v[158:161], v[198:201], v[108:111]
	v_mfma_f32_16x16x32_bf16 v[104:107], v[166:169], v[198:201], v[104:107]
	v_mfma_f32_16x16x32_bf16 v[92:95], v[158:161], v[212:215], v[92:95]
	v_mfma_f32_16x16x32_bf16 v[88:91], v[166:169], v[212:215], v[88:91]
	v_mfma_f32_16x16x32_bf16 v[76:79], v[158:161], v[220:223], v[76:79]
	v_mfma_f32_16x16x32_bf16 v[72:75], v[166:169], v[220:223], v[72:75]
	s_setprio 0
	s_setprio 1
	v_mfma_f32_16x16x32_bf16 v[116:119], v[170:173], v[186:189], v[116:119]
	v_mfma_f32_16x16x32_bf16 v[112:115], v[178:181], v[186:189], v[112:115]
	v_mfma_f32_16x16x32_bf16 v[100:103], v[170:173], v[194:197], v[100:103]
	v_mfma_f32_16x16x32_bf16 v[96:99], v[178:181], v[194:197], v[96:99]
	v_mfma_f32_16x16x32_bf16 v[84:87], v[170:173], v[208:211], v[84:87]
	v_mfma_f32_16x16x32_bf16 v[80:83], v[178:181], v[208:211], v[80:83]
	v_mfma_f32_16x16x32_bf16 v[68:71], v[170:173], v[216:219], v[68:71]
	v_mfma_f32_16x16x32_bf16 v[64:67], v[178:181], v[216:219], v[64:67]
	v_mfma_f32_16x16x32_bf16 v[116:119], v[174:177], v[190:193], v[116:119]
	v_mfma_f32_16x16x32_bf16 v[112:115], v[182:185], v[190:193], v[112:115]
	v_mfma_f32_16x16x32_bf16 v[100:103], v[174:177], v[198:201], v[100:103]
	v_mfma_f32_16x16x32_bf16 v[96:99], v[182:185], v[198:201], v[96:99]
	v_mfma_f32_16x16x32_bf16 v[84:87], v[174:177], v[212:215], v[84:87]
	v_mfma_f32_16x16x32_bf16 v[80:83], v[182:185], v[212:215], v[80:83]
	v_mfma_f32_16x16x32_bf16 v[68:71], v[174:177], v[220:223], v[68:71]
	v_mfma_f32_16x16x32_bf16 v[64:67], v[182:185], v[220:223], v[64:67]
	s_setprio 0
	s_barrier
	s_cmp_eq_u32 s93, 12
	s_cbranch_scc0 .Lp4_noss
	v_lshl_add_u32 v248, s88, 8, v154
	v_ashrrev_i32_e32 v249, 31, v248
	v_lshlrev_b64 v[248:249], 6, v[248:249]
	v_and_or_b32 v248, v204, 48, v248
	v_lshl_add_u64 v[248:249], s[90:91], 0, v[248:249]
	global_load_dwordx4 v[232:235], v[248:249], off
	global_load_dwordx4 v[236:239], v[248:249], off offset:1024
	global_load_dwordx4 v[240:243], v[248:249], off offset:2048
	global_load_dwordx4 v[244:247], v[248:249], off offset:3072
; #define PG8_STAGE(bufoff, gbase, voff) do { _Pragma("unroll") for (int _i = 0; _i < 2; ++_i) \
;         __builtin_amdgcn_global_load_lds((const unsigned*)((const char*)(gbase) + (voff)[_i]), (PG8_LAS unsigned*)(lds + (bufoff) + ldsw + _i * 8192), 16, 0, 0); } while (0)
; #define PG8_LDA(dst, b, h) do { _Pragma("unroll") for (int m = 0; m < 4; ++m) _Pragma("unroll") for (int k = 0; k < 2; ++k) dst[m][k] = *(const PG8_LAS bf16x8*)(lds + PG8_SA(b, h) + aoff + m * 2048 + k * 1024); } while (0)
; #define PG8_LDB(dst, b, h) do { _Pragma("unroll") for (int n = 0; n < 2; ++n) _Pragma("unroll") for (int k = 0; k < 2; ++k) dst[n][k] = *(const PG8_LAS bf16x8*)(lds + PG8_SB(b, h) + boff + n * 2048 + k * 1024); } while (0)
; #define PG8_WAIT_V(n) asm volatile("s_waitcnt vmcnt(" #n ")" ::: "memory")
; #define PG8_WAIT_L(n) asm volatile("s_waitcnt lgkmcnt(" #n ")" ::: "memory")
;     __device__ __forceinline__ void operator()(const f32x4 (&acc)[2][2][4][2], const Unit& u, int wr, int wc, int fr, int fq) const {
;         const int row0 = u.pm * BM + wr * 64 + fr, col0 = u.pn * BM + wc * 32 + 8 * fq;
; #pragma unroll
;         for (int ai = 0; ai < 2; ++ai)
; #pragma unroll
;             for (int m = 0; m < 4; ++m) {
;                 const int row = row0 + ai * HALF + m * 16;
;                 const f32x4* sp = (const f32x4*)(ss + (size_t)row * 16);
;                 const f32x4 a0 = sp[0], a1 = sp[1], a2 = sp[2], a3 = sp[3];
;                 const float tot = ((a0.x + a0.y) + (a0.z + a0.w)) + ((a1.x + a1.y) + (a1.z + a1.w)) + ((a2.x + a2.y) + (a2.z + a2.w)) + ((a3.x + a3.y) + (a3.z + a3.w));
;                 const float rs = rsqrtf(tot * (1.0f / 1024.0f) + 1e-6f);
; template <class Epi, class Sched, bool ALIGN_EPI = false, bool SP2 = false>
; __device__ __forceinline__ void gemm_phase(PG8_LAS unsigned char* lds, const Gemm g, const Sched& S, const Epi& E) {
;     ...
;             PG8_LDB(B0, 1, 0); PG8_LDB(B1, 1, 1); PG8_SCHED; PG8_LDA(At, 1, 0); PG8_STAGE(PG8_SA(0, 1), a2 + hstep, voffA);
;             PG8_WAIT_V(8); PG8_WAIT_L(0); PG8_BAR; PG8_MMA(0, 0, At, B0); PG8_MMA(0, 1, At, B1); PG8_BAR; PG8_SCHED;
;             PG8_LDA(At, 1, 1); PG8_STAGE(PG8_SB(1, 0), b3, voffB); PG8_STAGE(PG8_SB(1, 1), b3 + hstep, voffB); PG8_STAGE(PG8_SA(1, 0), a3, voffA);
;             PG8_WAIT_V(8); PG8_WAIT_L(0); PG8_BAR; PG8_MMA(1, 0, At, B0); PG8_MMA(1, 1, At, B1); PG8_BAR; PG8_SCHED;
.Lp4_noss:
	s_add_i32 s42, s76, s48
	v_lshl_add_u64 v[202:203], v[202:203], 0, s[34:35]
	s_mov_b32 m0, s42
	ds_read_b128 v[186:189], v157 offset:49152
	ds_read_b128 v[190:193], v157 offset:50176
	ds_read_b128 v[194:197], v157 offset:51200
	ds_read_b128 v[198:201], v157 offset:52224
	ds_read_b128 v[208:211], v157 offset:53248
	ds_read_b128 v[212:215], v157 offset:54272
	ds_read_b128 v[216:219], v157 offset:55296
	ds_read_b128 v[220:223], v157 offset:56320
	global_load_lds_dwordx4 v[202:203], off
	s_add_i32 m0, s42, 0x2000
	s_add_u32 s26, s26, 0x40080
	v_lshl_add_u64 v[202:203], v[224:225], 0, s[34:35]
	s_addc_u32 s27, s27, 0
	s_add_i32 s42, s77, s48
	global_load_lds_dwordx4 v[202:203], off
	v_lshl_add_u64 v[202:203], s[26:27], 0, v[138:139]
	s_mov_b32 m0, s42
	s_nop 0
	global_load_lds_dwordx4 v[202:203], off
	v_lshl_add_u64 v[202:203], s[26:27], 0, v[128:129]
	s_add_i32 m0, s42, 0x2000
	s_nop 0
	global_load_lds_dwordx4 v[202:203], off
	v_lshl_add_u64 v[202:203], v[226:227], 0, s[34:35]
	s_mov_b32 m0, s55
	s_nop 0
	global_load_lds_dwordx4 v[202:203], off
	v_lshl_add_u64 v[202:203], v[228:229], 0, s[34:35]
	s_mov_b32 m0, s58
	s_nop 0
	global_load_lds_dwordx4 v[202:203], off
	s_waitcnt vmcnt(8)
	s_waitcnt lgkmcnt(0)
	s_barrier
	s_setprio 1
	s_waitcnt lgkmcnt(0)
	v_mfma_f32_16x16x32_bf16 v[60:63], v[150:153], v[186:189], v[60:63]
	v_mfma_f32_16x16x32_bf16 v[56:59], v[162:165], v[186:189], v[56:59]
	v_mfma_f32_16x16x32_bf16 v[44:47], v[150:153], v[194:197], v[44:47]
	v_mfma_f32_16x16x32_bf16 v[40:43], v[162:165], v[194:197], v[40:43]
	v_mfma_f32_16x16x32_bf16 v[28:31], v[150:153], v[208:211], v[28:31]
	v_mfma_f32_16x16x32_bf16 v[24:27], v[162:165], v[208:211], v[24:27]
	v_mfma_f32_16x16x32_bf16 v[12:15], v[150:153], v[216:219], v[12:15]
	v_mfma_f32_16x16x32_bf16 v[8:11], v[162:165], v[216:219], v[8:11]
	v_mfma_f32_16x16x32_bf16 v[60:63], v[158:161], v[190:193], v[60:63]
	v_mfma_f32_16x16x32_bf16 v[56:59], v[166:169], v[190:193], v[56:59]
	v_mfma_f32_16x16x32_bf16 v[44:47], v[158:161], v[198:201], v[44:47]
	v_mfma_f32_16x16x32_bf16 v[40:43], v[166:169], v[198:201], v[40:43]
	v_mfma_f32_16x16x32_bf16 v[28:31], v[158:161], v[212:215], v[28:31]
	v_mfma_f32_16x16x32_bf16 v[24:27], v[166:169], v[212:215], v[24:27]
	v_mfma_f32_16x16x32_bf16 v[12:15], v[158:161], v[220:223], v[12:15]
	v_mfma_f32_16x16x32_bf16 v[8:11], v[166:169], v[220:223], v[8:11]
	s_setprio 0
	s_setprio 1
	v_mfma_f32_16x16x32_bf16 v[52:55], v[170:173], v[186:189], v[52:55]
	v_mfma_f32_16x16x32_bf16 v[48:51], v[178:181], v[186:189], v[48:51]
	v_mfma_f32_16x16x32_bf16 v[36:39], v[170:173], v[194:197], v[36:39]
	v_mfma_f32_16x16x32_bf16 v[32:35], v[178:181], v[194:197], v[32:35]
	v_mfma_f32_16x16x32_bf16 v[20:23], v[170:173], v[208:211], v[20:23]
	v_mfma_f32_16x16x32_bf16 v[16:19], v[178:181], v[208:211], v[16:19]
	v_mfma_f32_16x16x32_bf16 v[4:7], v[170:173], v[216:219], v[4:7]
	v_mfma_f32_16x16x32_bf16 v[0:3], v[178:181], v[216:219], v[0:3]
	v_mfma_f32_16x16x32_bf16 v[52:55], v[174:177], v[190:193], v[52:55]
	v_mfma_f32_16x16x32_bf16 v[48:51], v[182:185], v[190:193], v[48:51]
	v_mfma_f32_16x16x32_bf16 v[36:39], v[174:177], v[198:201], v[36:39]
	v_mfma_f32_16x16x32_bf16 v[32:35], v[182:185], v[198:201], v[32:35]
	v_mfma_f32_16x16x32_bf16 v[20:23], v[174:177], v[212:215], v[20:23]
	v_mfma_f32_16x16x32_bf16 v[16:19], v[182:185], v[212:215], v[16:19]
	v_mfma_f32_16x16x32_bf16 v[4:7], v[174:177], v[220:223], v[4:7]
	v_mfma_f32_16x16x32_bf16 v[0:3], v[182:185], v[220:223], v[0:3]
	s_setprio 0
	s_barrier
	s_add_i32 s93, s93, 2
	s_add_u32 s24, s24, 0x100
	s_addc_u32 s25, s25, 0
	s_add_u32 s36, s36, 0x100
	s_addc_u32 s37, s37, 0
	s_cmp_gt_u32 s93, 13
	s_cbranch_scc0 .LBB0_1152
	v_readlane_b32 s76, v250, 21
	v_readlane_b32 s92, v250, 23
	s_and_b64 vcc, exec, s[40:41]
	v_readlane_b32 s77, v250, 22
	v_readlane_b32 s93, v250, 24
	s_cbranch_vccz .LBB0_1155
	s_barrier
.LBB0_1155:
	v_lshl_add_u32 v152, s88, 8, v154
	v_ashrrev_i32_e32 v153, 31, v152
	v_lshlrev_b64 v[176:177], 6, v[152:153]
	v_and_or_b32 v176, v204, 48, v176
	v_lshl_add_u64 v[176:177], s[90:91], 0, v[176:177]
	v_mov_b32_e32 v178, 0x2000
	v_mov_b32_e32 v179, 0
	v_lshl_add_u64 v[178:179], v[176:177], 0, v[178:179]
	global_load_dwordx4 v[196:199], v[178:179], off
	global_load_dwordx4 v[208:211], v[178:179], off offset:1024
	global_load_dwordx4 v[212:215], v[178:179], off offset:2048
	global_load_dwordx4 v[216:219], v[178:179], off offset:3072
	v_bfe_u32 v228, v204, 2, 4
	v_and_b32_e32 v229, -16, v154
	v_or_b32_e32 v229, v229, v228
	v_lshl_add_u32 v152, s88, 8, v229
	v_ashrrev_i32_e32 v153, 31, v152
	v_and_b32_e32 v229, 3, v204
	v_lshlrev_b32_e32 v230, 3, v229
	v_and_b32_e32 v231, -32, v156
	v_or_b32_e32 v230, v230, v231
	v_lshl_add_u32 v228, v229, 4, v228
	v_lshlrev_b32_e32 v228, 2, v228
	v_lshl_or_b32 v150, s30, 8, v230
	v_ashrrev_i32_e32 v151, 31, v150
	v_lshlrev_b64 v[150:151], 1, v[150:151]
	s_mov_b64 s[24:25], -1
	v_lshlrev_b64 v[160:161], 13, v[152:153]
	v_lshl_add_u64 v[160:161], s[78:79], 0, v[160:161]
	v_lshl_add_u64 v[160:161], v[160:161], 0, v[150:151]
	s_waitcnt vmcnt(10)
; __device__ __forceinline__ unsigned cvt_pk_bf16(float lo, float hi) { unsigned r; asm volatile("v_cvt_pk_bf16_f32 %0, %1, %2" : "=v"(r) : "v"(lo), "v"(hi)); return r; }
;     __device__ __forceinline__ void operator()(const f32x4 (&acc)[2][2][4][2], const Unit& u, int wr, int wc, int fr, int fq) const {
;     ...
;                 const int row = row0 + ai * HALF + m * 16;
;                 const f32x4* sp = (const f32x4*)(ss + (size_t)row * 16);
;                 const f32x4 a0 = sp[0], a1 = sp[1], a2 = sp[2], a3 = sp[3];
;                 const float tot = ((a0.x + a0.y) + (a0.z + a0.w)) + ((a1.x + a1.y) + (a1.z + a1.w)) + ((a2.x + a2.y) + (a2.z + a2.w)) + ((a3.x + a3.y) + (a3.z + a3.w));
;                 const float rs = rsqrtf(tot * (1.0f / 1024.0f) + 1e-6f);
;                 bf16_t* rowp = O + (size_t)row * ldc + col0;
; #pragma unroll
;                 for (int bj = 0; bj < 2; ++bj) {
;                     f32x4 v0 = acc[ai][bj][m][0] * rs, v1 = acc[ai][bj][m][1] * rs;
;                     if (ACT == 1) {
; #pragma unroll
;                         for (int e = 0; e < 4; ++e) { float a = fmaxf(v0[e], 0.f); v0[e] = a * a; float b = fmaxf(v1[e], 0.f); v1[e] = b * b; }
;                     }
;                     u32x4 w; w.x = cvt_pk_bf16(v0[0], v0[1]); w.y = cvt_pk_bf16(v0[2], v0[3]); w.z = cvt_pk_bf16(v1[0], v1[1]); w.w = cvt_pk_bf16(v1[2], v1[3]);
;                     *(u32x4*)(rowp + bj * HALF) = w;
	v_mov_b32_e32 v180, v232
	v_mov_b32_e32 v181, v233
	v_mov_b32_e32 v182, v234
	v_mov_b32_e32 v183, v235
	v_mov_b32_e32 v184, v236
	v_mov_b32_e32 v185, v237
	v_mov_b32_e32 v186, v238
	v_mov_b32_e32 v187, v239
	v_mov_b32_e32 v188, v240
	v_mov_b32_e32 v189, v241
	v_mov_b32_e32 v190, v242
	v_mov_b32_e32 v191, v243
	v_mov_b32_e32 v192, v244
	v_mov_b32_e32 v193, v245
	v_mov_b32_e32 v194, v246
	v_mov_b32_e32 v195, v247
	v_add_f32_e32 v180, v180, v181
	v_add_f32_e32 v182, v182, v183
	v_add_f32_e32 v184, v184, v185
	v_add_f32_e32 v186, v186, v187
	v_add_f32_e32 v188, v188, v189
	v_add_f32_e32 v190, v190, v191
	v_add_f32_e32 v192, v192, v193
	v_add_f32_e32 v194, v194, v195
	v_add_f32_e32 v180, v180, v182
	v_add_f32_e32 v184, v184, v186
	v_add_f32_e32 v188, v188, v190
	v_add_f32_e32 v192, v192, v194
	v_mov_b32_e32 v181, v180
	v_mov_b32_e32 v185, v184
	v_mov_b32_e32 v189, v188
	v_mov_b32_e32 v193, v192
	s_nop 1
	v_permlane16_swap_b32_e32 v180, v181
	v_permlane16_swap_b32_e32 v184, v185
	v_permlane16_swap_b32_e32 v188, v189
	v_permlane16_swap_b32_e32 v192, v193
	v_add_f32_e32 v180, v180, v181
	v_add_f32_e32 v184, v184, v185
	v_add_f32_e32 v188, v188, v189
	v_add_f32_e32 v192, v192, v193
	v_mov_b32_e32 v181, v180
	v_mov_b32_e32 v185, v184
	v_mov_b32_e32 v189, v188
	v_mov_b32_e32 v193, v192
	s_nop 1
	v_permlane32_swap_b32_e32 v180, v181
	v_permlane32_swap_b32_e32 v184, v185
	v_permlane32_swap_b32_e32 v188, v189
	v_permlane32_swap_b32_e32 v192, v193
	v_add_f32_e32 v180, v180, v181
	v_add_f32_e32 v184, v184, v185
	v_add_f32_e32 v188, v188, v189
	v_add_f32_e32 v192, v192, v193
	v_fmamk_f32 v180, v180, 0x3a800000, v137
	v_cmp_gt_f32_e32 vcc, s4, v180
	v_mul_f32_e32 v181, 0x4b800000, v180
	s_nop 0
	v_cndmask_b32_e32 v180, v180, v181, vcc
	v_rsq_f32_e32 v180, v180
	s_nop 0
	v_mul_f32_e32 v181, 0x45800000, v180
	v_cndmask_b32_e32 v180, v180, v181, vcc
	v_fmamk_f32 v184, v184, 0x3a800000, v137
	v_cmp_gt_f32_e32 vcc, s4, v184
	v_mul_f32_e32 v185, 0x4b800000, v184
	s_nop 0
	v_cndmask_b32_e32 v184, v184, v185, vcc
	v_rsq_f32_e32 v184, v184
	s_nop 0
	v_mul_f32_e32 v185, 0x45800000, v184
	v_cndmask_b32_e32 v184, v184, v185, vcc
	v_fmamk_f32 v188, v188, 0x3a800000, v137
	v_cmp_gt_f32_e32 vcc, s4, v188
	v_mul_f32_e32 v189, 0x4b800000, v188
	s_nop 0
	v_cndmask_b32_e32 v188, v188, v189, vcc
	v_rsq_f32_e32 v188, v188
	s_nop 0
	v_mul_f32_e32 v189, 0x45800000, v188
	v_cndmask_b32_e32 v188, v188, v189, vcc
	v_fmamk_f32 v192, v192, 0x3a800000, v137
	v_cmp_gt_f32_e32 vcc, s4, v192
	v_mul_f32_e32 v193, 0x4b800000, v192
	s_nop 0
	v_cndmask_b32_e32 v192, v192, v193, vcc
	v_rsq_f32_e32 v192, v192
	s_nop 0
	v_mul_f32_e32 v193, 0x45800000, v192
	v_cndmask_b32_e32 v192, v192, v193, vcc
	v_mov_b32_e32 v158, v180
	v_pk_mul_f32 v[120:121], v[120:121], v[158:159] op_sel_hi:[1,0]
	v_pk_mul_f32 v[124:125], v[124:125], v[158:159] op_sel_hi:[1,0]
	v_pk_mul_f32 v[122:123], v[122:123], v[158:159] op_sel_hi:[1,0]
	v_max_f32_e32 v120, 0, v120
	v_pk_mul_f32 v[126:127], v[126:127], v[158:159] op_sel_hi:[1,0]
	v_mul_f32_e32 v153, v120, v120
	v_max_f32_e32 v120, 0, v125
	v_max_f32_e32 v121, 0, v121
	v_max_f32_e32 v122, 0, v122
	v_max_f32_e32 v124, 0, v124
	v_mul_f32_e32 v120, v120, v120
	v_mul_f32_e32 v125, v121, v121
	v_max_f32_e32 v121, 0, v126
	v_mul_f32_e32 v126, v122, v122
	v_max_f32_e32 v122, 0, v127
	v_max_f32_e32 v123, 0, v123
	v_pk_mul_f32 v[112:113], v[112:113], v[158:159] op_sel_hi:[1,0]
	v_mul_f32_e32 v124, v124, v124
	v_mul_f32_e32 v121, v121, v121
	v_mul_f32_e32 v122, v122, v122
	v_mul_f32_e32 v123, v123, v123
	v_cvt_pk_bf16_f32 v120, v124, v120
	v_pk_mul_f32 v[116:117], v[116:117], v[158:159] op_sel_hi:[1,0]
	v_pk_mul_f32 v[114:115], v[114:115], v[158:159] op_sel_hi:[1,0]
	v_max_f32_e32 v112, 0, v112
	v_cvt_pk_bf16_f32 v121, v121, v122
	v_cvt_pk_bf16_f32 v122, v153, v125
	v_cvt_pk_bf16_f32 v123, v126, v123
	ds_bpermute_b32 v220, v228, v120
	ds_bpermute_b32 v221, v228, v121
	ds_bpermute_b32 v222, v228, v122
	ds_bpermute_b32 v223, v228, v123
	v_pk_mul_f32 v[118:119], v[118:119], v[158:159] op_sel_hi:[1,0]
	v_max_f32_e32 v113, 0, v113
	v_mul_f32_e32 v120, v112, v112
	v_max_f32_e32 v112, 0, v117
	v_max_f32_e32 v114, 0, v114
	v_max_f32_e32 v116, 0, v116
	v_mul_f32_e32 v112, v112, v112
	v_mul_f32_e32 v117, v113, v113
	v_max_f32_e32 v113, 0, v118
	v_mul_f32_e32 v118, v114, v114
	v_max_f32_e32 v114, 0, v119
	v_max_f32_e32 v115, 0, v115
	v_mul_f32_e32 v116, v116, v116
	v_mul_f32_e32 v113, v113, v113
	v_mul_f32_e32 v114, v114, v114
	v_mul_f32_e32 v115, v115, v115
	v_cvt_pk_bf16_f32 v112, v116, v112
	v_cvt_pk_bf16_f32 v113, v113, v114
	v_cvt_pk_bf16_f32 v114, v120, v117
	v_cvt_pk_bf16_f32 v115, v118, v115
	ds_bpermute_b32 v224, v228, v112
	ds_bpermute_b32 v225, v228, v113
	ds_bpermute_b32 v226, v228, v114
	ds_bpermute_b32 v227, v228, v115
	s_waitcnt lgkmcnt(4)
	global_store_dwordx4 v[160:161], v[220:223], off
	s_waitcnt lgkmcnt(0)
; __device__ __forceinline__ unsigned cvt_pk_bf16(float lo, float hi) { unsigned r; asm volatile("v_cvt_pk_bf16_f32 %0, %1, %2" : "=v"(r) : "v"(lo), "v"(hi)); return r; }
;     __device__ __forceinline__ void operator()(const f32x4 (&acc)[2][2][4][2], const Unit& u, int wr, int wc, int fr, int fq) const {
;     ...
;                 const int row = row0 + ai * HALF + m * 16;
;                 const f32x4* sp = (const f32x4*)(ss + (size_t)row * 16);
;                 const f32x4 a0 = sp[0], a1 = sp[1], a2 = sp[2], a3 = sp[3];
;                 const float tot = ((a0.x + a0.y) + (a0.z + a0.w)) + ((a1.x + a1.y) + (a1.z + a1.w)) + ((a2.x + a2.y) + (a2.z + a2.w)) + ((a3.x + a3.y) + (a3.z + a3.w));
;                 const float rs = rsqrtf(tot * (1.0f / 1024.0f) + 1e-6f);
;                 bf16_t* rowp = O + (size_t)row * ldc + col0;
; #pragma unroll
;                 for (int bj = 0; bj < 2; ++bj) {
;                     f32x4 v0 = acc[ai][bj][m][0] * rs, v1 = acc[ai][bj][m][1] * rs;
;                     if (ACT == 1) {
; #pragma unroll
;                         for (int e = 0; e < 4; ++e) { float a = fmaxf(v0[e], 0.f); v0[e] = a * a; float b = fmaxf(v1[e], 0.f); v1[e] = b * b; }
;                     }
;                     u32x4 w; w.x = cvt_pk_bf16(v0[0], v0[1]); w.y = cvt_pk_bf16(v0[2], v0[3]); w.z = cvt_pk_bf16(v1[0], v1[1]); w.w = cvt_pk_bf16(v1[2], v1[3]);
;                     *(u32x4*)(rowp + bj * HALF) = w;
	global_store_dwordx4 v[160:161], v[224:227], off offset:256
	s_nop 1
	v_or_b32_e32 v112, 16, v152
	v_ashrrev_i32_e32 v113, 31, v112
	v_lshlrev_b64 v[112:113], 13, v[112:113]
	v_lshl_add_u64 v[112:113], s[78:79], 0, v[112:113]
	v_lshl_add_u64 v[112:113], v[112:113], 0, v[150:151]
	v_mov_b32_e32 v114, v184
	v_pk_mul_f32 v[104:105], v[104:105], v[114:115] op_sel_hi:[1,0]
	v_pk_mul_f32 v[108:109], v[108:109], v[114:115] op_sel_hi:[1,0]
	v_pk_mul_f32 v[106:107], v[106:107], v[114:115] op_sel_hi:[1,0]
	v_max_f32_e32 v104, 0, v104
	v_pk_mul_f32 v[110:111], v[110:111], v[114:115] op_sel_hi:[1,0]
	v_mul_f32_e32 v115, v104, v104
	v_max_f32_e32 v104, 0, v109
	v_max_f32_e32 v105, 0, v105
	v_max_f32_e32 v106, 0, v106
	v_max_f32_e32 v108, 0, v108
	v_mul_f32_e32 v104, v104, v104
	v_mul_f32_e32 v109, v105, v105
	v_max_f32_e32 v105, 0, v110
	v_mul_f32_e32 v110, v106, v106
	v_max_f32_e32 v106, 0, v111
	v_max_f32_e32 v107, 0, v107
	v_pk_mul_f32 v[96:97], v[96:97], v[114:115] op_sel_hi:[1,0]
	v_mul_f32_e32 v108, v108, v108
	v_mul_f32_e32 v105, v105, v105
	v_mul_f32_e32 v106, v106, v106
	v_mul_f32_e32 v107, v107, v107
	v_cvt_pk_bf16_f32 v104, v108, v104
	v_pk_mul_f32 v[100:101], v[100:101], v[114:115] op_sel_hi:[1,0]
	v_pk_mul_f32 v[98:99], v[98:99], v[114:115] op_sel_hi:[1,0]
	v_max_f32_e32 v96, 0, v96
	v_cvt_pk_bf16_f32 v105, v105, v106
	v_cvt_pk_bf16_f32 v106, v115, v109
	v_cvt_pk_bf16_f32 v107, v110, v107
	ds_bpermute_b32 v220, v228, v104
	ds_bpermute_b32 v221, v228, v105
	ds_bpermute_b32 v222, v228, v106
	ds_bpermute_b32 v223, v228, v107
	v_pk_mul_f32 v[102:103], v[102:103], v[114:115] op_sel_hi:[1,0]
	v_max_f32_e32 v97, 0, v97
	v_mul_f32_e32 v104, v96, v96
	v_max_f32_e32 v96, 0, v101
	v_max_f32_e32 v98, 0, v98
	v_max_f32_e32 v100, 0, v100
	v_mul_f32_e32 v96, v96, v96
	v_mul_f32_e32 v101, v97, v97
	v_max_f32_e32 v97, 0, v102
	v_mul_f32_e32 v102, v98, v98
	v_max_f32_e32 v98, 0, v103
	v_max_f32_e32 v99, 0, v99
	v_mul_f32_e32 v100, v100, v100
	v_mul_f32_e32 v97, v97, v97
	v_mul_f32_e32 v98, v98, v98
	v_mul_f32_e32 v99, v99, v99
	v_cvt_pk_bf16_f32 v96, v100, v96
	v_cvt_pk_bf16_f32 v97, v97, v98
	v_cvt_pk_bf16_f32 v98, v104, v101
	v_cvt_pk_bf16_f32 v99, v102, v99
	ds_bpermute_b32 v224, v228, v96
	ds_bpermute_b32 v225, v228, v97
	ds_bpermute_b32 v226, v228, v98
	ds_bpermute_b32 v227, v228, v99
	s_waitcnt lgkmcnt(4)
	global_store_dwordx4 v[112:113], v[220:223], off
	s_waitcnt lgkmcnt(0)
	global_store_dwordx4 v[112:113], v[224:227], off offset:256
	s_nop 1
	v_or_b32_e32 v96, 32, v152
	v_ashrrev_i32_e32 v97, 31, v96
	v_lshlrev_b64 v[96:97], 13, v[96:97]
	v_lshl_add_u64 v[96:97], s[78:79], 0, v[96:97]
	v_lshl_add_u64 v[96:97], v[96:97], 0, v[150:151]
	v_mov_b32_e32 v98, v188
	v_pk_mul_f32 v[88:89], v[88:89], v[98:99] op_sel_hi:[1,0]
	v_pk_mul_f32 v[92:93], v[92:93], v[98:99] op_sel_hi:[1,0]
	v_pk_mul_f32 v[90:91], v[90:91], v[98:99] op_sel_hi:[1,0]
	v_max_f32_e32 v88, 0, v88
	v_pk_mul_f32 v[94:95], v[94:95], v[98:99] op_sel_hi:[1,0]
	v_mul_f32_e32 v99, v88, v88
	v_max_f32_e32 v88, 0, v93
	v_max_f32_e32 v89, 0, v89
	v_max_f32_e32 v90, 0, v90
	v_max_f32_e32 v92, 0, v92
	v_mul_f32_e32 v88, v88, v88
	v_mul_f32_e32 v93, v89, v89
	v_max_f32_e32 v89, 0, v94
	v_mul_f32_e32 v94, v90, v90
	v_max_f32_e32 v90, 0, v95
	v_max_f32_e32 v91, 0, v91
	v_pk_mul_f32 v[80:81], v[80:81], v[98:99] op_sel_hi:[1,0]
	v_mul_f32_e32 v92, v92, v92
	v_mul_f32_e32 v89, v89, v89
	v_mul_f32_e32 v90, v90, v90
	v_mul_f32_e32 v91, v91, v91
	v_cvt_pk_bf16_f32 v88, v92, v88
	v_pk_mul_f32 v[84:85], v[84:85], v[98:99] op_sel_hi:[1,0]
	v_pk_mul_f32 v[82:83], v[82:83], v[98:99] op_sel_hi:[1,0]
	v_max_f32_e32 v80, 0, v80
	v_cvt_pk_bf16_f32 v89, v89, v90
	v_cvt_pk_bf16_f32 v90, v99, v93
	v_cvt_pk_bf16_f32 v91, v94, v91
	ds_bpermute_b32 v220, v228, v88
	ds_bpermute_b32 v221, v228, v89
	ds_bpermute_b32 v222, v228, v90
	ds_bpermute_b32 v223, v228, v91
	v_pk_mul_f32 v[86:87], v[86:87], v[98:99] op_sel_hi:[1,0]
	v_max_f32_e32 v81, 0, v81
	v_mul_f32_e32 v88, v80, v80
	v_max_f32_e32 v80, 0, v85
	v_max_f32_e32 v82, 0, v82
	v_max_f32_e32 v84, 0, v84
	v_mul_f32_e32 v80, v80, v80
	v_mul_f32_e32 v85, v81, v81
	v_max_f32_e32 v81, 0, v86
	v_mul_f32_e32 v86, v82, v82
	v_max_f32_e32 v82, 0, v87
	v_max_f32_e32 v83, 0, v83
	v_mul_f32_e32 v84, v84, v84
	v_mul_f32_e32 v81, v81, v81
	v_mul_f32_e32 v82, v82, v82
	v_mul_f32_e32 v83, v83, v83
	v_cvt_pk_bf16_f32 v80, v84, v80
	v_cvt_pk_bf16_f32 v81, v81, v82
	v_cvt_pk_bf16_f32 v82, v88, v85
	v_cvt_pk_bf16_f32 v83, v86, v83
	ds_bpermute_b32 v224, v228, v80
	ds_bpermute_b32 v225, v228, v81
	ds_bpermute_b32 v226, v228, v82
	ds_bpermute_b32 v227, v228, v83
	s_waitcnt lgkmcnt(4)
	global_store_dwordx4 v[96:97], v[220:223], off
	s_waitcnt lgkmcnt(0)
; __device__ __forceinline__ unsigned cvt_pk_bf16(float lo, float hi) { unsigned r; asm volatile("v_cvt_pk_bf16_f32 %0, %1, %2" : "=v"(r) : "v"(lo), "v"(hi)); return r; }
;     __device__ __forceinline__ void operator()(const f32x4 (&acc)[2][2][4][2], const Unit& u, int wr, int wc, int fr, int fq) const {
;     ...
;                 const int row = row0 + ai * HALF + m * 16;
;                 const f32x4* sp = (const f32x4*)(ss + (size_t)row * 16);
;                 const f32x4 a0 = sp[0], a1 = sp[1], a2 = sp[2], a3 = sp[3];
;                 const float tot = ((a0.x + a0.y) + (a0.z + a0.w)) + ((a1.x + a1.y) + (a1.z + a1.w)) + ((a2.x + a2.y) + (a2.z + a2.w)) + ((a3.x + a3.y) + (a3.z + a3.w));
;                 const float rs = rsqrtf(tot * (1.0f / 1024.0f) + 1e-6f);
;                 bf16_t* rowp = O + (size_t)row * ldc + col0;
; #pragma unroll
;                 for (int bj = 0; bj < 2; ++bj) {
;                     f32x4 v0 = acc[ai][bj][m][0] * rs, v1 = acc[ai][bj][m][1] * rs;
;                     if (ACT == 1) {
; #pragma unroll
;                         for (int e = 0; e < 4; ++e) { float a = fmaxf(v0[e], 0.f); v0[e] = a * a; float b = fmaxf(v1[e], 0.f); v1[e] = b * b; }
;                     }
;                     u32x4 w; w.x = cvt_pk_bf16(v0[0], v0[1]); w.y = cvt_pk_bf16(v0[2], v0[3]); w.z = cvt_pk_bf16(v1[0], v1[1]); w.w = cvt_pk_bf16(v1[2], v1[3]);
;                     *(u32x4*)(rowp + bj * HALF) = w;
	global_store_dwordx4 v[96:97], v[224:227], off offset:256
	s_nop 1
	v_or_b32_e32 v80, 48, v152
	v_ashrrev_i32_e32 v81, 31, v80
	v_lshlrev_b64 v[80:81], 13, v[80:81]
	v_lshl_add_u64 v[80:81], s[78:79], 0, v[80:81]
	v_lshl_add_u64 v[80:81], v[80:81], 0, v[150:151]
	v_mov_b32_e32 v82, v192
	v_pk_mul_f32 v[72:73], v[72:73], v[82:83] op_sel_hi:[1,0]
	v_pk_mul_f32 v[76:77], v[76:77], v[82:83] op_sel_hi:[1,0]
	v_pk_mul_f32 v[74:75], v[74:75], v[82:83] op_sel_hi:[1,0]
	v_max_f32_e32 v72, 0, v72
	v_pk_mul_f32 v[78:79], v[78:79], v[82:83] op_sel_hi:[1,0]
	v_mul_f32_e32 v83, v72, v72
	v_max_f32_e32 v72, 0, v77
	v_max_f32_e32 v73, 0, v73
	v_max_f32_e32 v74, 0, v74
	v_max_f32_e32 v76, 0, v76
	v_mul_f32_e32 v72, v72, v72
	v_mul_f32_e32 v77, v73, v73
	v_max_f32_e32 v73, 0, v78
	v_mul_f32_e32 v78, v74, v74
	v_max_f32_e32 v74, 0, v79
	v_max_f32_e32 v75, 0, v75
	v_pk_mul_f32 v[64:65], v[64:65], v[82:83] op_sel_hi:[1,0]
	v_mul_f32_e32 v76, v76, v76
	v_mul_f32_e32 v73, v73, v73
	v_mul_f32_e32 v74, v74, v74
	v_mul_f32_e32 v75, v75, v75
	v_cvt_pk_bf16_f32 v72, v76, v72
	v_pk_mul_f32 v[68:69], v[68:69], v[82:83] op_sel_hi:[1,0]
	v_pk_mul_f32 v[66:67], v[66:67], v[82:83] op_sel_hi:[1,0]
	v_max_f32_e32 v64, 0, v64
	v_cvt_pk_bf16_f32 v73, v73, v74
	v_cvt_pk_bf16_f32 v74, v83, v77
	v_cvt_pk_bf16_f32 v75, v78, v75
	ds_bpermute_b32 v220, v228, v72
	ds_bpermute_b32 v221, v228, v73
	ds_bpermute_b32 v222, v228, v74
	ds_bpermute_b32 v223, v228, v75
	v_pk_mul_f32 v[70:71], v[70:71], v[82:83] op_sel_hi:[1,0]
	v_max_f32_e32 v65, 0, v65
	v_mul_f32_e32 v72, v64, v64
	v_max_f32_e32 v64, 0, v69
	v_max_f32_e32 v66, 0, v66
	v_max_f32_e32 v68, 0, v68
	v_mul_f32_e32 v64, v64, v64
	v_mul_f32_e32 v69, v65, v65
	v_max_f32_e32 v65, 0, v70
	v_mul_f32_e32 v70, v66, v66
	v_max_f32_e32 v66, 0, v71
	v_max_f32_e32 v67, 0, v67
	v_mul_f32_e32 v68, v68, v68
	v_mul_f32_e32 v65, v65, v65
	v_mul_f32_e32 v66, v66, v66
	v_mul_f32_e32 v67, v67, v67
	v_cvt_pk_bf16_f32 v64, v68, v64
	v_cvt_pk_bf16_f32 v65, v65, v66
	v_cvt_pk_bf16_f32 v66, v72, v69
	v_cvt_pk_bf16_f32 v67, v70, v67
	ds_bpermute_b32 v224, v228, v64
	ds_bpermute_b32 v225, v228, v65
	ds_bpermute_b32 v226, v228, v66
	ds_bpermute_b32 v227, v228, v67
	s_waitcnt lgkmcnt(4)
	global_store_dwordx4 v[80:81], v[220:223], off
	s_waitcnt lgkmcnt(0)
	global_store_dwordx4 v[80:81], v[224:227], off offset:256
	s_nop 1
	v_add_u32_e32 v64, 0x80, v152
	v_ashrrev_i32_e32 v65, 31, v64
	v_lshlrev_b64 v[64:65], 13, v[64:65]
	v_lshl_add_u64 v[64:65], s[78:79], 0, v[64:65]
	v_lshl_add_u64 v[64:65], v[64:65], 0, v[150:151]
	s_waitcnt vmcnt(8)
	v_add_f32_e32 v196, v196, v197
	v_add_f32_e32 v198, v198, v199
	v_add_f32_e32 v208, v208, v209
	v_add_f32_e32 v210, v210, v211
	v_add_f32_e32 v212, v212, v213
	v_add_f32_e32 v214, v214, v215
	v_add_f32_e32 v216, v216, v217
	v_add_f32_e32 v218, v218, v219
	v_add_f32_e32 v196, v196, v198
	v_add_f32_e32 v208, v208, v210
	v_add_f32_e32 v212, v212, v214
	v_add_f32_e32 v216, v216, v218
	v_mov_b32_e32 v197, v196
	v_mov_b32_e32 v209, v208
	v_mov_b32_e32 v213, v212
	v_mov_b32_e32 v217, v216
	s_nop 1
	v_permlane16_swap_b32_e32 v196, v197
	v_permlane16_swap_b32_e32 v208, v209
	v_permlane16_swap_b32_e32 v212, v213
	v_permlane16_swap_b32_e32 v216, v217
	v_add_f32_e32 v196, v196, v197
	v_add_f32_e32 v208, v208, v209
	v_add_f32_e32 v212, v212, v213
	v_add_f32_e32 v216, v216, v217
	v_mov_b32_e32 v197, v196
	v_mov_b32_e32 v209, v208
	v_mov_b32_e32 v213, v212
	v_mov_b32_e32 v217, v216
	s_nop 1
	v_permlane32_swap_b32_e32 v196, v197
	v_permlane32_swap_b32_e32 v208, v209
	v_permlane32_swap_b32_e32 v212, v213
	v_permlane32_swap_b32_e32 v216, v217
	v_add_f32_e32 v196, v196, v197
	v_add_f32_e32 v208, v208, v209
	v_add_f32_e32 v212, v212, v213
	v_add_f32_e32 v216, v216, v217
	v_fmamk_f32 v196, v196, 0x3a800000, v137
	v_cmp_gt_f32_e32 vcc, s4, v196
	v_mul_f32_e32 v197, 0x4b800000, v196
	s_nop 0
	v_cndmask_b32_e32 v196, v196, v197, vcc
	v_rsq_f32_e32 v196, v196
	s_nop 0
	v_mul_f32_e32 v197, 0x45800000, v196
	v_cndmask_b32_e32 v196, v196, v197, vcc
	v_fmamk_f32 v208, v208, 0x3a800000, v137
	v_cmp_gt_f32_e32 vcc, s4, v208
	v_mul_f32_e32 v209, 0x4b800000, v208
	s_nop 0
	v_cndmask_b32_e32 v208, v208, v209, vcc
	v_rsq_f32_e32 v208, v208
	s_nop 0
	v_mul_f32_e32 v209, 0x45800000, v208
	v_cndmask_b32_e32 v208, v208, v209, vcc
	v_fmamk_f32 v212, v212, 0x3a800000, v137
	v_cmp_gt_f32_e32 vcc, s4, v212
	v_mul_f32_e32 v213, 0x4b800000, v212
	s_nop 0
	v_cndmask_b32_e32 v212, v212, v213, vcc
	v_rsq_f32_e32 v212, v212
	s_nop 0
	v_mul_f32_e32 v213, 0x45800000, v212
	v_cndmask_b32_e32 v212, v212, v213, vcc
	v_fmamk_f32 v216, v216, 0x3a800000, v137
	v_cmp_gt_f32_e32 vcc, s4, v216
	v_mul_f32_e32 v217, 0x4b800000, v216
	s_nop 0
	v_cndmask_b32_e32 v216, v216, v217, vcc
	v_rsq_f32_e32 v216, v216
	s_nop 0
	v_mul_f32_e32 v217, 0x45800000, v216
	v_cndmask_b32_e32 v216, v216, v217, vcc
	v_mov_b32_e32 v66, v196
	v_pk_mul_f32 v[56:57], v[56:57], v[66:67] op_sel_hi:[1,0]
	v_pk_mul_f32 v[60:61], v[60:61], v[66:67] op_sel_hi:[1,0]
	v_pk_mul_f32 v[58:59], v[58:59], v[66:67] op_sel_hi:[1,0]
	v_max_f32_e32 v56, 0, v56
	v_pk_mul_f32 v[62:63], v[62:63], v[66:67] op_sel_hi:[1,0]
	v_mul_f32_e32 v67, v56, v56
	v_max_f32_e32 v56, 0, v61
	v_max_f32_e32 v57, 0, v57
	v_max_f32_e32 v58, 0, v58
	v_max_f32_e32 v60, 0, v60
	v_mul_f32_e32 v56, v56, v56
	v_mul_f32_e32 v61, v57, v57
	v_max_f32_e32 v57, 0, v62
	v_mul_f32_e32 v62, v58, v58
	v_max_f32_e32 v58, 0, v63
	v_max_f32_e32 v59, 0, v59
	v_pk_mul_f32 v[48:49], v[48:49], v[66:67] op_sel_hi:[1,0]
	v_mul_f32_e32 v60, v60, v60
	v_mul_f32_e32 v57, v57, v57
	v_mul_f32_e32 v58, v58, v58
	v_mul_f32_e32 v59, v59, v59
	v_cvt_pk_bf16_f32 v56, v60, v56
	v_pk_mul_f32 v[52:53], v[52:53], v[66:67] op_sel_hi:[1,0]
	v_pk_mul_f32 v[50:51], v[50:51], v[66:67] op_sel_hi:[1,0]
	v_max_f32_e32 v48, 0, v48
	v_cvt_pk_bf16_f32 v57, v57, v58
	v_cvt_pk_bf16_f32 v58, v67, v61
	v_cvt_pk_bf16_f32 v59, v62, v59
	ds_bpermute_b32 v220, v228, v56
	ds_bpermute_b32 v221, v228, v57
	ds_bpermute_b32 v222, v228, v58
	ds_bpermute_b32 v223, v228, v59
	v_pk_mul_f32 v[54:55], v[54:55], v[66:67] op_sel_hi:[1,0]
	v_max_f32_e32 v49, 0, v49
	v_mul_f32_e32 v56, v48, v48
	v_max_f32_e32 v48, 0, v53
	v_max_f32_e32 v50, 0, v50
	v_max_f32_e32 v52, 0, v52
	v_mul_f32_e32 v48, v48, v48
	v_mul_f32_e32 v53, v49, v49
	v_max_f32_e32 v49, 0, v54
	v_mul_f32_e32 v54, v50, v50
	v_max_f32_e32 v50, 0, v55
	v_max_f32_e32 v51, 0, v51
	v_mul_f32_e32 v52, v52, v52
	v_mul_f32_e32 v49, v49, v49
	v_mul_f32_e32 v50, v50, v50
	v_mul_f32_e32 v51, v51, v51
	v_cvt_pk_bf16_f32 v48, v52, v48
	v_cvt_pk_bf16_f32 v49, v49, v50
	v_cvt_pk_bf16_f32 v50, v56, v53
	v_cvt_pk_bf16_f32 v51, v54, v51
	ds_bpermute_b32 v224, v228, v48
	ds_bpermute_b32 v225, v228, v49
	ds_bpermute_b32 v226, v228, v50
	ds_bpermute_b32 v227, v228, v51
	s_waitcnt lgkmcnt(4)
; __device__ __forceinline__ unsigned cvt_pk_bf16(float lo, float hi) { unsigned r; asm volatile("v_cvt_pk_bf16_f32 %0, %1, %2" : "=v"(r) : "v"(lo), "v"(hi)); return r; }
;     __device__ __forceinline__ void operator()(const f32x4 (&acc)[2][2][4][2], const Unit& u, int wr, int wc, int fr, int fq) const {
;     ...
;                 const int row = row0 + ai * HALF + m * 16;
;                 const f32x4* sp = (const f32x4*)(ss + (size_t)row * 16);
;                 const f32x4 a0 = sp[0], a1 = sp[1], a2 = sp[2], a3 = sp[3];
;                 const float tot = ((a0.x + a0.y) + (a0.z + a0.w)) + ((a1.x + a1.y) + (a1.z + a1.w)) + ((a2.x + a2.y) + (a2.z + a2.w)) + ((a3.x + a3.y) + (a3.z + a3.w));
;                 const float rs = rsqrtf(tot * (1.0f / 1024.0f) + 1e-6f);
;                 bf16_t* rowp = O + (size_t)row * ldc + col0;
; #pragma unroll
;                 for (int bj = 0; bj < 2; ++bj) {
;                     f32x4 v0 = acc[ai][bj][m][0] * rs, v1 = acc[ai][bj][m][1] * rs;
;                     if (ACT == 1) {
; #pragma unroll
;                         for (int e = 0; e < 4; ++e) { float a = fmaxf(v0[e], 0.f); v0[e] = a * a; float b = fmaxf(v1[e], 0.f); v1[e] = b * b; }
;                     }
;                     u32x4 w; w.x = cvt_pk_bf16(v0[0], v0[1]); w.y = cvt_pk_bf16(v0[2], v0[3]); w.z = cvt_pk_bf16(v1[0], v1[1]); w.w = cvt_pk_bf16(v1[2], v1[3]);
;                     *(u32x4*)(rowp + bj * HALF) = w;
	global_store_dwordx4 v[64:65], v[220:223], off
	s_waitcnt lgkmcnt(0)
	global_store_dwordx4 v[64:65], v[224:227], off offset:256
	s_nop 1
	v_add_u32_e32 v48, 0x90, v152
	v_ashrrev_i32_e32 v49, 31, v48
	v_lshlrev_b64 v[48:49], 13, v[48:49]
	v_lshl_add_u64 v[48:49], s[78:79], 0, v[48:49]
	v_lshl_add_u64 v[48:49], v[48:49], 0, v[150:151]
	v_mov_b32_e32 v50, v208
	v_pk_mul_f32 v[40:41], v[40:41], v[50:51] op_sel_hi:[1,0]
	v_pk_mul_f32 v[44:45], v[44:45], v[50:51] op_sel_hi:[1,0]
	v_pk_mul_f32 v[42:43], v[42:43], v[50:51] op_sel_hi:[1,0]
	v_max_f32_e32 v40, 0, v40
	v_pk_mul_f32 v[46:47], v[46:47], v[50:51] op_sel_hi:[1,0]
	v_mul_f32_e32 v51, v40, v40
	v_max_f32_e32 v40, 0, v45
	v_max_f32_e32 v41, 0, v41
	v_max_f32_e32 v42, 0, v42
	v_max_f32_e32 v44, 0, v44
	v_mul_f32_e32 v40, v40, v40
	v_mul_f32_e32 v45, v41, v41
	v_max_f32_e32 v41, 0, v46
	v_mul_f32_e32 v46, v42, v42
	v_max_f32_e32 v42, 0, v47
	v_max_f32_e32 v43, 0, v43
	v_pk_mul_f32 v[32:33], v[32:33], v[50:51] op_sel_hi:[1,0]
	v_mul_f32_e32 v44, v44, v44
	v_mul_f32_e32 v41, v41, v41
	v_mul_f32_e32 v42, v42, v42
	v_mul_f32_e32 v43, v43, v43
	v_cvt_pk_bf16_f32 v40, v44, v40
	v_pk_mul_f32 v[36:37], v[36:37], v[50:51] op_sel_hi:[1,0]
	v_pk_mul_f32 v[34:35], v[34:35], v[50:51] op_sel_hi:[1,0]
	v_max_f32_e32 v32, 0, v32
	v_cvt_pk_bf16_f32 v41, v41, v42
	v_cvt_pk_bf16_f32 v42, v51, v45
	v_cvt_pk_bf16_f32 v43, v46, v43
	ds_bpermute_b32 v220, v228, v40
	ds_bpermute_b32 v221, v228, v41
	ds_bpermute_b32 v222, v228, v42
	ds_bpermute_b32 v223, v228, v43
	v_pk_mul_f32 v[38:39], v[38:39], v[50:51] op_sel_hi:[1,0]
	v_max_f32_e32 v33, 0, v33
	v_mul_f32_e32 v40, v32, v32
	v_max_f32_e32 v32, 0, v37
	v_max_f32_e32 v34, 0, v34
	v_max_f32_e32 v36, 0, v36
	v_mul_f32_e32 v32, v32, v32
	v_mul_f32_e32 v37, v33, v33
	v_max_f32_e32 v33, 0, v38
	v_mul_f32_e32 v38, v34, v34
	v_max_f32_e32 v34, 0, v39
	v_max_f32_e32 v35, 0, v35
	v_mul_f32_e32 v36, v36, v36
	v_mul_f32_e32 v33, v33, v33
	v_mul_f32_e32 v34, v34, v34
	v_mul_f32_e32 v35, v35, v35
	v_cvt_pk_bf16_f32 v32, v36, v32
	v_cvt_pk_bf16_f32 v33, v33, v34
	v_cvt_pk_bf16_f32 v34, v40, v37
	v_cvt_pk_bf16_f32 v35, v38, v35
	ds_bpermute_b32 v224, v228, v32
	ds_bpermute_b32 v225, v228, v33
	ds_bpermute_b32 v226, v228, v34
	ds_bpermute_b32 v227, v228, v35
	s_waitcnt lgkmcnt(4)
	global_store_dwordx4 v[48:49], v[220:223], off
	s_waitcnt lgkmcnt(0)
	global_store_dwordx4 v[48:49], v[224:227], off offset:256
	s_nop 1
	v_add_u32_e32 v32, 0xa0, v152
	v_ashrrev_i32_e32 v33, 31, v32
	v_lshlrev_b64 v[32:33], 13, v[32:33]
	v_lshl_add_u64 v[32:33], s[78:79], 0, v[32:33]
	v_lshl_add_u64 v[32:33], v[32:33], 0, v[150:151]
	v_mov_b32_e32 v34, v212
	v_pk_mul_f32 v[24:25], v[24:25], v[34:35] op_sel_hi:[1,0]
	v_pk_mul_f32 v[28:29], v[28:29], v[34:35] op_sel_hi:[1,0]
	v_pk_mul_f32 v[26:27], v[26:27], v[34:35] op_sel_hi:[1,0]
	v_max_f32_e32 v24, 0, v24
	v_pk_mul_f32 v[30:31], v[30:31], v[34:35] op_sel_hi:[1,0]
	v_mul_f32_e32 v35, v24, v24
	v_max_f32_e32 v24, 0, v29
	v_max_f32_e32 v25, 0, v25
	v_max_f32_e32 v26, 0, v26
	v_max_f32_e32 v28, 0, v28
	v_mul_f32_e32 v24, v24, v24
	v_mul_f32_e32 v29, v25, v25
	v_max_f32_e32 v25, 0, v30
	v_mul_f32_e32 v30, v26, v26
	v_max_f32_e32 v26, 0, v31
	v_max_f32_e32 v27, 0, v27
	v_pk_mul_f32 v[16:17], v[16:17], v[34:35] op_sel_hi:[1,0]
	v_mul_f32_e32 v28, v28, v28
	v_mul_f32_e32 v25, v25, v25
	v_mul_f32_e32 v26, v26, v26
	v_mul_f32_e32 v27, v27, v27
	v_cvt_pk_bf16_f32 v24, v28, v24
	v_pk_mul_f32 v[20:21], v[20:21], v[34:35] op_sel_hi:[1,0]
	v_pk_mul_f32 v[18:19], v[18:19], v[34:35] op_sel_hi:[1,0]
	v_max_f32_e32 v16, 0, v16
	v_cvt_pk_bf16_f32 v25, v25, v26
	v_cvt_pk_bf16_f32 v26, v35, v29
	v_cvt_pk_bf16_f32 v27, v30, v27
	ds_bpermute_b32 v220, v228, v24
	ds_bpermute_b32 v221, v228, v25
	ds_bpermute_b32 v222, v228, v26
	ds_bpermute_b32 v223, v228, v27
	v_pk_mul_f32 v[22:23], v[22:23], v[34:35] op_sel_hi:[1,0]
	v_max_f32_e32 v17, 0, v17
	v_mul_f32_e32 v24, v16, v16
	v_max_f32_e32 v16, 0, v21
	v_max_f32_e32 v18, 0, v18
	v_max_f32_e32 v20, 0, v20
	v_mul_f32_e32 v16, v16, v16
	v_mul_f32_e32 v21, v17, v17
	v_max_f32_e32 v17, 0, v22
	v_mul_f32_e32 v22, v18, v18
	v_max_f32_e32 v18, 0, v23
	v_max_f32_e32 v19, 0, v19
	v_mul_f32_e32 v20, v20, v20
	v_mul_f32_e32 v17, v17, v17
	v_mul_f32_e32 v18, v18, v18
	v_mul_f32_e32 v19, v19, v19
	v_cvt_pk_bf16_f32 v16, v20, v16
	v_cvt_pk_bf16_f32 v17, v17, v18
	v_cvt_pk_bf16_f32 v18, v24, v21
	v_cvt_pk_bf16_f32 v19, v22, v19
	ds_bpermute_b32 v224, v228, v16
	ds_bpermute_b32 v225, v228, v17
	ds_bpermute_b32 v226, v228, v18
	ds_bpermute_b32 v227, v228, v19
	s_waitcnt lgkmcnt(4)
	global_store_dwordx4 v[32:33], v[220:223], off
	s_waitcnt lgkmcnt(0)
	global_store_dwordx4 v[32:33], v[224:227], off offset:256
	s_nop 1
	v_add_u32_e32 v16, 0xb0, v152
	v_ashrrev_i32_e32 v17, 31, v16
	v_lshlrev_b64 v[16:17], 13, v[16:17]
	v_lshl_add_u64 v[16:17], s[78:79], 0, v[16:17]
	v_lshl_add_u64 v[16:17], v[16:17], 0, v[150:151]
	v_mov_b32_e32 v18, v216
	v_pk_mul_f32 v[8:9], v[8:9], v[18:19] op_sel_hi:[1,0]
	v_pk_mul_f32 v[12:13], v[12:13], v[18:19] op_sel_hi:[1,0]
	v_pk_mul_f32 v[10:11], v[10:11], v[18:19] op_sel_hi:[1,0]
	v_max_f32_e32 v8, 0, v8
	v_pk_mul_f32 v[14:15], v[14:15], v[18:19] op_sel_hi:[1,0]
	v_mul_f32_e32 v19, v8, v8
	v_max_f32_e32 v8, 0, v13
	v_max_f32_e32 v9, 0, v9
	v_max_f32_e32 v10, 0, v10
	v_max_f32_e32 v12, 0, v12
	v_mul_f32_e32 v8, v8, v8
	v_mul_f32_e32 v13, v9, v9
	v_max_f32_e32 v9, 0, v14
	v_mul_f32_e32 v14, v10, v10
	v_max_f32_e32 v10, 0, v15
	v_max_f32_e32 v11, 0, v11
	v_pk_mul_f32 v[2:3], v[2:3], v[18:19] op_sel_hi:[1,0]
	v_pk_mul_f32 v[0:1], v[0:1], v[18:19] op_sel_hi:[1,0]
	v_mul_f32_e32 v12, v12, v12
	v_mul_f32_e32 v9, v9, v9
	v_mul_f32_e32 v10, v10, v10
	v_mul_f32_e32 v11, v11, v11
	v_cvt_pk_bf16_f32 v8, v12, v8
	v_pk_mul_f32 v[6:7], v[6:7], v[18:19] op_sel_hi:[1,0]
	v_pk_mul_f32 v[4:5], v[4:5], v[18:19] op_sel_hi:[1,0]
	v_max_f32_e32 v0, 0, v0
	v_max_f32_e32 v1, 0, v1
	v_max_f32_e32 v2, 0, v2
	v_cvt_pk_bf16_f32 v9, v9, v10
	v_cvt_pk_bf16_f32 v10, v19, v13
	v_cvt_pk_bf16_f32 v11, v14, v11
	ds_bpermute_b32 v220, v228, v8
	ds_bpermute_b32 v221, v228, v9
	ds_bpermute_b32 v222, v228, v10
	ds_bpermute_b32 v223, v228, v11
	v_max_f32_e32 v3, 0, v3
	v_max_f32_e32 v4, 0, v4
	v_mul_f32_e32 v8, v0, v0
	v_max_f32_e32 v0, 0, v5
	v_mul_f32_e32 v5, v1, v1
	v_max_f32_e32 v1, 0, v6
	v_mul_f32_e32 v6, v2, v2
	v_max_f32_e32 v2, 0, v7
	v_mul_f32_e32 v0, v0, v0
	v_mul_f32_e32 v1, v1, v1
	v_mul_f32_e32 v2, v2, v2
	v_mul_f32_e32 v3, v3, v3
	s_andn2_b64 vcc, exec, s[38:39]
	v_mul_f32_e32 v4, v4, v4
	v_cvt_pk_bf16_f32 v0, v4, v0
	v_cvt_pk_bf16_f32 v1, v1, v2
	v_cvt_pk_bf16_f32 v2, v8, v5
	v_cvt_pk_bf16_f32 v3, v6, v3
	ds_bpermute_b32 v224, v228, v0
	ds_bpermute_b32 v225, v228, v1
	ds_bpermute_b32 v226, v228, v2
	ds_bpermute_b32 v227, v228, v3
	s_waitcnt lgkmcnt(4)
	global_store_dwordx4 v[16:17], v[220:223], off
	s_waitcnt lgkmcnt(0)
	global_store_dwordx4 v[16:17], v[224:227], off offset:256
	s_cbranch_vccnz .LBB0_1144
	s_andn2_b64 vcc, exec, s[0:1]
	s_cbranch_vccnz .LBB0_1143
	s_barrier
	s_branch .LBB0_1143
